# tail-fill conversion with three more sites (M1, M3 and LRU pass-1 last rounds, 192 idle workgroups each); P0 keeps only gate-up layer-0 and the AB input projection weights
# speedup vs baseline: 1.0038x; 1.0038x over previous
.LBB0_36:
	s_lshl_b32 s0, s24, 3
	s_add_i32 s98, s25, s0
	s_lshl_b32 s99, s33, 3
	s_mov_b32 s100, 0x13a80
	s_cmpk_eq_i32 s33, 0x100
	s_cselect_b32 s100, 0x4400, s100
	s_mov_b32 s101, 0

.LBB0_40:
	s_mov_b32 s90, 0x0
	s_cmp_ge_u32 s98, 0x2b00
	s_cselect_b32 s90, 0xd700, s90
	s_cmp_ge_u32 s98, 0x4400
	s_cselect_b32 s90, 0x6800, s90
	s_cmp_ge_u32 s98, 0x5980
	s_cselect_b32 s90, 0xc180, s90
	s_cmp_ge_u32 s98, 0x6180
	s_cselect_b32 s90, 0xffffc980, s90
	s_cmp_ge_u32 s98, 0x8c80
	s_cselect_b32 s90, 0x3500, s90
	s_cmp_ge_u32 s98, 0xa200
	s_cselect_b32 s90, 0xffffb400, s90
	s_cmp_ge_u32 s98, 0xcd00
	s_cselect_b32 s90, 0xa00, s90
	s_cmp_ge_u32 s98, 0xe280
	s_cselect_b32 s90, 0x4080, s90
	s_cmp_ge_u32 s98, 0xee80
	s_cselect_b32 s90, 0x4880, s90
	s_cmp_ge_u32 s98, 0xf200
	s_cselect_b32 s90, 0x3d00, s90
	s_cmp_ge_u32 s98, 0xfa00
	s_cselect_b32 s90, 0xffff8700, s90
	s_cmp_ge_u32 s98, 0x12500
	s_cselect_b32 s90, 0xffffc780, s90
	s_add_i32 s90, s90, s98
	s_add_i32 s19, s90, 0xfffec680
	s_lshl_b32 s20, s90, 4
	s_lshl_b32 s22, s90, 5
	s_add_i32 s80, s90, 0xffff5400
	s_cmp_gt_i32 s90, 0xabff
	s_mov_b64 s[2:3], -1
	s_cbranch_scc0 .LBB0_134
	s_cmp_gt_u32 s90, 0x101ff
	s_cbranch_scc0 .LBB0_115
	s_cmp_gt_u32 s90, 0x11aff
	s_cbranch_scc0 .LBB0_80
	s_cmp_gt_u32 s90, 0x122ff
	s_cbranch_scc0 .LBB0_77
	s_cmp_gt_u32 s90, 0x12eff
	s_cbranch_scc0 .LBB0_58
	s_cmp_gt_u32 s90, 0x136ff
	s_cbranch_scc0 .LBB0_55
	s_cmp_gt_u32 s90, 0x1387f
	s_cbranch_scc0 .LBB0_52
	s_cmp_gt_u32 s90, 0x1397f
	s_cbranch_scc0 .LBB0_49
	s_lshr_b32 s2, s19, 3
	s_bfe_u32 s3, s19, 0x30003
	v_readlane_b32 s52, v252, 18
	s_bitcmp0_b32 s90, 6
	v_readlane_b32 s60, v252, 26
	v_readlane_b32 s61, v252, 27
	v_readlane_b32 s64, v252, 30
	v_readlane_b32 s65, v252, 31
	s_cselect_b32 s10, s61, s65
	s_cselect_b32 s11, s60, s64
	s_lshr_b32 s6, s19, 4
	s_and_b32 s6, s6, 0xffffff8
	s_or_b32 s6, s6, s3
	s_lshl_b64 s[8:9], s[6:7], 16
	s_add_u32 s8, s11, s8
	s_mov_b32 s3, s7
	s_addc_u32 s9, s10, s9
	s_lshl_b64 s[2:3], s[2:3], 15
	s_add_u32 s2, s13, s2
	s_addc_u32 s3, s14, s3
	s_and_b32 s10, s20, 64
	v_add_u32_e32 v2, s10, v1
	v_ashrrev_i32_e32 v3, 31, v2
	s_and_b32 s11, s22, 0x60
	v_lshlrev_b64 v[2:3], 9, v[2:3]
	v_lshl_add_u64 v[2:3], s[8:9], 0, v[2:3]
	s_lshl_b32 s6, s11, 2
	v_lshl_add_u64 v[2:3], v[2:3], 0, s[6:7]
	v_lshlrev_b32_e32 v34, 2, v112
	v_lshl_add_u64 v[30:31], v[2:3], 0, v[34:35]
	s_movk_i32 s6, 0x2000
	v_add_co_u32_e32 v10, vcc, s6, v30
	s_movk_i32 s6, 0x4000
	s_nop 0
	v_addc_co_u32_e32 v11, vcc, 0, v31, vcc
	v_add_co_u32_e32 v18, vcc, s6, v30
	s_movk_i32 s6, 0x6000
	s_nop 0
	v_addc_co_u32_e32 v19, vcc, 0, v31, vcc
	v_add_co_u32_e32 v26, vcc, s6, v30
	global_load_dwordx4 v[2:5], v[30:31], off nt
	s_nop 0
	v_addc_co_u32_e32 v27, vcc, 0, v31, vcc
	global_load_dwordx4 v[6:9], v[10:11], off offset:-4096 nt
	s_nop 0
	global_load_dwordx4 v[10:13], v[10:11], off nt
	s_nop 0
	global_load_dwordx4 v[14:17], v[18:19], off offset:-4096 nt
	s_nop 0
	global_load_dwordx4 v[18:21], v[18:19], off nt
	s_nop 0
	global_load_dwordx4 v[22:25], v[26:27], off offset:-4096 nt
	s_nop 0
	global_load_dwordx4 v[26:29], v[26:27], off nt
	s_movk_i32 s6, 0x7000
	v_add_co_u32_e32 v30, vcc, s6, v30
	v_add_u32_e32 v134, v115, v118
	s_nop 0
	v_addc_co_u32_e32 v31, vcc, 0, v31, vcc
	global_load_dwordx4 v[30:33], v[30:31], off nt
	v_add_u32_e32 v135, 0x420, v134
	v_add_u32_e32 v136, 0x428, v134
	v_add_u32_e32 v137, 0x840, v134
	v_add_u32_e32 v138, 0x848, v134
	v_add_u32_e32 v139, 0xc60, v134
	v_add_u32_e32 v140, 0xc68, v134
	v_add_u32_e32 v141, 0x1080, v134
	v_add_u32_e32 v142, 0x1088, v134
	v_add_u32_e32 v143, 0x14a0, v134
	v_add_u32_e32 v144, 0x14a8, v134
	v_add_u32_e32 v145, 0x18c0, v134
	v_add_u32_e32 v146, 0x18c8, v134
	v_add_u32_e32 v147, 0x1ce0, v134
	v_add_u32_e32 v148, 0x1ce8, v134
	s_lshl_b32 s6, s10, 1
	v_add_u32_e32 v116, s11, v1
	s_add_u32 s2, s2, s6
	v_ashrrev_i32_e32 v117, 31, v116
	s_addc_u32 s3, s3, 0
	v_lshlrev_b32_e32 v34, 1, v114
	v_lshlrev_b64 v[116:117], 8, v[116:117]
	v_lshl_add_u64 v[132:133], s[2:3], 0, v[34:35]
	v_readlane_b32 s53, v252, 19
	v_readlane_b32 s54, v252, 20
	v_readlane_b32 s55, v252, 21
	v_readlane_b32 s56, v252, 22
	v_readlane_b32 s57, v252, 23
	v_readlane_b32 s58, v252, 24
	v_readlane_b32 s59, v252, 25
	v_readlane_b32 s62, v252, 28
	v_readlane_b32 s63, v252, 29
	v_readlane_b32 s66, v252, 32
	v_readlane_b32 s67, v252, 33
	s_mov_b64 s[2:3], 0
	s_waitcnt vmcnt(7)
	ds_write2_b32 v134, v2, v3 offset1:1
	ds_write2_b32 v134, v4, v5 offset0:2 offset1:3
	s_waitcnt vmcnt(6)
	ds_write2_b32 v135, v6, v7 offset1:1
	ds_write2_b32 v136, v8, v9 offset1:1
	s_waitcnt vmcnt(5)
	ds_write2_b32 v137, v10, v11 offset1:1
	ds_write2_b32 v138, v12, v13 offset1:1
	s_waitcnt vmcnt(4)
	ds_write2_b32 v139, v14, v15 offset1:1
	ds_write2_b32 v140, v16, v17 offset1:1
	s_waitcnt vmcnt(3)
	ds_write2_b32 v141, v18, v19 offset1:1
	ds_write2_b32 v142, v20, v21 offset1:1
	s_waitcnt vmcnt(2)
	ds_write2_b32 v143, v22, v23 offset1:1
	ds_write2_b32 v144, v24, v25 offset1:1
	s_waitcnt vmcnt(1)
	ds_write2_b32 v145, v26, v27 offset1:1
	ds_write2_b32 v146, v28, v29 offset1:1
	s_waitcnt vmcnt(0)
	ds_write2_b32 v147, v30, v31 offset1:1
	ds_write2_b32 v148, v32, v33 offset1:1
	s_waitcnt lgkmcnt(0)
	ds_read2_b32 v[6:7], v122 offset0:33 offset1:41
	ds_read2_b32 v[8:9], v122 offset1:8
	ds_read2_b32 v[10:11], v122 offset0:66 offset1:74
	ds_read2_b32 v[12:13], v122 offset0:99 offset1:107
	ds_read2_b32 v[14:15], v122 offset0:132 offset1:140
	ds_read2_b32 v[16:17], v122 offset0:165 offset1:173
	ds_read2_b32 v[18:19], v122 offset0:198 offset1:206
	ds_read2_b32 v[20:21], v122 offset0:231 offset1:239
	v_lshl_add_u64 v[22:23], v[132:133], 0, v[116:117]
	s_waitcnt lgkmcnt(6)
	v_cvt_pk_bf16_f32 v2, v8, v6
	s_waitcnt lgkmcnt(4)
	v_cvt_pk_bf16_f32 v3, v10, v12
	s_waitcnt lgkmcnt(2)
	v_cvt_pk_bf16_f32 v4, v14, v16
	s_waitcnt lgkmcnt(0)
	v_cvt_pk_bf16_f32 v5, v18, v20
	global_store_dwordx4 v[22:23], v[2:5], off nt
	v_cvt_pk_bf16_f32 v6, v9, v7
	v_cvt_pk_bf16_f32 v7, v11, v13
	v_add_u32_e32 v2, s11, v119
	v_ashrrev_i32_e32 v3, 31, v2
	v_cvt_pk_bf16_f32 v8, v15, v17
	v_cvt_pk_bf16_f32 v9, v19, v21
	v_lshlrev_b64 v[2:3], 8, v[2:3]
	ds_read2_b32 v[10:11], v122 offset0:49 offset1:57
	ds_read2_b32 v[12:13], v122 offset0:16 offset1:24
	ds_read2_b32 v[14:15], v122 offset0:82 offset1:90
	ds_read2_b32 v[16:17], v122 offset0:115 offset1:123
	ds_read2_b32 v[18:19], v122 offset0:148 offset1:156
	ds_read2_b32 v[20:21], v122 offset0:181 offset1:189
	ds_read2_b32 v[22:23], v122 offset0:214 offset1:222
	ds_read2_b32 v[24:25], v122 offset0:247 offset1:255
	v_lshl_add_u64 v[2:3], v[132:133], 0, v[2:3]
	global_store_dwordx4 v[2:3], v[6:9], off nt
	s_waitcnt lgkmcnt(6)
	v_cvt_pk_bf16_f32 v2, v12, v10
	s_waitcnt lgkmcnt(4)
	v_cvt_pk_bf16_f32 v3, v14, v16
	v_add_u32_e32 v6, s11, v120
	v_ashrrev_i32_e32 v7, 31, v6
	v_lshlrev_b64 v[6:7], 8, v[6:7]
	s_waitcnt lgkmcnt(2)
	v_cvt_pk_bf16_f32 v4, v18, v20
	s_waitcnt lgkmcnt(0)
	v_cvt_pk_bf16_f32 v5, v22, v24
	v_lshl_add_u64 v[6:7], v[132:133], 0, v[6:7]
	global_store_dwordx4 v[6:7], v[2:5], off nt
	v_add_u32_e32 v6, s11, v121
	v_ashrrev_i32_e32 v7, 31, v6
	v_lshlrev_b64 v[6:7], 8, v[6:7]
	v_cvt_pk_bf16_f32 v2, v13, v11
	v_cvt_pk_bf16_f32 v3, v15, v17
	v_cvt_pk_bf16_f32 v4, v19, v21
	v_cvt_pk_bf16_f32 v5, v23, v25
	v_lshl_add_u64 v[6:7], v[132:133], 0, v[6:7]
	global_store_dwordx4 v[6:7], v[2:5], off nt
	s_waitcnt lgkmcnt(0)

.Lmy_cvt_done:
	s_cmp_eq_u32 s101, 0
	s_cbranch_scc1 .LBB0_151
	s_cmp_eq_u32 s101, 1
	s_cbranch_scc1 .Lmy_back_p2
	s_cmp_eq_u32 s101, 2
	s_cbranch_scc1 .Lmy_back_p5
	s_cmp_eq_u32 s101, 7
	s_cbranch_scc1 .Lmy_back_m1
	s_branch .Lmy_h1_back

.LBB0_302:
	s_cmpk_lg_i32 s33, 0x100
	s_cbranch_scc1 .Lmy_skip_p2
	s_cmp_lt_u32 s76, 108
	s_cbranch_scc1 .Lmy_skip_p2
	s_waitcnt vmcnt(0) lgkmcnt(0)
	s_barrier
	v_writelane_b32 v255, s0, 0
	v_writelane_b32 v255, s1, 1
	v_writelane_b32 v255, s2, 2
	v_writelane_b32 v255, s3, 3
	v_writelane_b32 v255, s4, 4
	v_writelane_b32 v255, s5, 5
	v_writelane_b32 v255, s6, 6
	v_writelane_b32 v255, s7, 7
	v_writelane_b32 v255, s8, 8
	v_writelane_b32 v255, s9, 9
	v_writelane_b32 v255, s10, 10
	v_writelane_b32 v255, s11, 11
	v_writelane_b32 v255, s12, 12
	v_writelane_b32 v255, s13, 13
	v_writelane_b32 v255, s14, 14
	v_writelane_b32 v255, s15, 15
	v_writelane_b32 v255, s16, 16
	v_writelane_b32 v255, s17, 17
	v_writelane_b32 v255, s18, 18
	v_writelane_b32 v255, s19, 19
	v_writelane_b32 v255, s20, 20
	v_writelane_b32 v255, s21, 21
	v_writelane_b32 v255, s22, 22
	v_writelane_b32 v255, s23, 23
	v_writelane_b32 v255, s26, 24
	v_writelane_b32 v255, s27, 25
	v_writelane_b32 v255, s34, 26
	v_writelane_b32 v255, s35, 27
	v_writelane_b32 v255, s36, 28
	v_writelane_b32 v255, s37, 29
	v_writelane_b32 v255, s38, 30
	v_writelane_b32 v255, s39, 31
	v_writelane_b32 v255, s40, 32
	v_writelane_b32 v255, s41, 33
	v_writelane_b32 v255, s42, 34
	v_writelane_b32 v255, s43, 35
	v_writelane_b32 v255, s44, 36
	v_writelane_b32 v255, s45, 37
	v_writelane_b32 v255, s46, 38
	v_writelane_b32 v255, s47, 39
	v_writelane_b32 v255, s48, 40
	v_writelane_b32 v255, s49, 41
	v_writelane_b32 v255, s50, 42
	v_writelane_b32 v255, s51, 43
	v_writelane_b32 v255, s52, 44
	v_writelane_b32 v255, s53, 45
	v_writelane_b32 v255, s54, 46
	v_writelane_b32 v255, s55, 47
	v_writelane_b32 v255, s56, 48
	v_writelane_b32 v255, s57, 49
	v_writelane_b32 v255, s58, 50
	v_writelane_b32 v255, s59, 51
	v_writelane_b32 v255, s60, 52
	v_writelane_b32 v255, s61, 53
	v_writelane_b32 v255, s62, 54
	v_writelane_b32 v255, s63, 55
	v_writelane_b32 v255, s64, 56
	v_writelane_b32 v255, s65, 57
	v_writelane_b32 v255, s66, 58
	v_writelane_b32 v255, s67, 59
	v_writelane_b32 v255, s68, 60
	v_writelane_b32 v255, s69, 61
	v_writelane_b32 v255, s70, 62
	v_writelane_b32 v255, s71, 63
	v_writelane_b32 v254, s76, 0
	v_writelane_b32 v254, s77, 1
	v_writelane_b32 v254, s80, 2
	v_writelane_b32 v254, s81, 3
	v_writelane_b32 v254, s82, 4
	v_writelane_b32 v254, s83, 5
	v_writelane_b32 v254, s84, 6
	v_writelane_b32 v254, s85, 7
	v_writelane_b32 v254, s86, 8
	v_writelane_b32 v254, s87, 9
	v_writelane_b32 v254, s88, 10
	v_writelane_b32 v254, s89, 11
	v_writelane_b32 v254, s90, 12
	v_writelane_b32 v254, s91, 13
	v_writelane_b32 v254, s92, 14
	v_writelane_b32 v254, s93, 15
	v_writelane_b32 v254, s94, 16
	v_writelane_b32 v254, s95, 17
	v_writelane_b32 v254, s96, 18
	v_writelane_b32 v254, s97, 19
	s_sub_i32 s98, s76, 108
	s_lshl_b32 s98, s98, 3
	s_add_i32 s98, s98, s25
	s_add_i32 s98, s98, 0x4400
	s_movk_i32 s99, 0x4a0
	s_mov_b32 s100, 0x7280
	s_mov_b32 s101, 1
	s_add_u32 s0, s78, 0xfffffef0
	s_addc_u32 s1, s79, -1
	s_load_dwordx8 s[36:43], s[0:1], 0x40
	s_waitcnt lgkmcnt(0)
	s_branch .Lmy_cvt_entry

.LBB0_716:
	s_waitcnt vmcnt(0)
	s_barrier
	s_cmpk_lg_i32 s33, 0x100
	s_cbranch_scc1 .Lmy_skip_p5
	s_cmp_lt_u32 s76, 164
	s_cbranch_scc1 .Lmy_skip_p5
	s_waitcnt vmcnt(0) lgkmcnt(0)
	s_barrier
	v_writelane_b32 v255, s0, 0
	v_writelane_b32 v255, s1, 1
	v_writelane_b32 v255, s2, 2
	v_writelane_b32 v255, s3, 3
	v_writelane_b32 v255, s4, 4
	v_writelane_b32 v255, s5, 5
	v_writelane_b32 v255, s6, 6
	v_writelane_b32 v255, s7, 7
	v_writelane_b32 v255, s8, 8
	v_writelane_b32 v255, s9, 9
	v_writelane_b32 v255, s10, 10
	v_writelane_b32 v255, s11, 11
	v_writelane_b32 v255, s12, 12
	v_writelane_b32 v255, s13, 13
	v_writelane_b32 v255, s14, 14
	v_writelane_b32 v255, s15, 15
	v_writelane_b32 v255, s16, 16
	v_writelane_b32 v255, s17, 17
	v_writelane_b32 v255, s18, 18
	v_writelane_b32 v255, s19, 19
	v_writelane_b32 v255, s20, 20
	v_writelane_b32 v255, s21, 21
	v_writelane_b32 v255, s22, 22
	v_writelane_b32 v255, s23, 23
	v_writelane_b32 v255, s26, 24
	v_writelane_b32 v255, s27, 25
	v_writelane_b32 v255, s34, 26
	v_writelane_b32 v255, s35, 27
	v_writelane_b32 v255, s36, 28
	v_writelane_b32 v255, s37, 29
	v_writelane_b32 v255, s38, 30
	v_writelane_b32 v255, s39, 31
	v_writelane_b32 v255, s40, 32
	v_writelane_b32 v255, s41, 33
	v_writelane_b32 v255, s42, 34
	v_writelane_b32 v255, s43, 35
	v_writelane_b32 v255, s44, 36
	v_writelane_b32 v255, s45, 37
	v_writelane_b32 v255, s46, 38
	v_writelane_b32 v255, s47, 39
	v_writelane_b32 v255, s48, 40
	v_writelane_b32 v255, s49, 41
	v_writelane_b32 v255, s50, 42
	v_writelane_b32 v255, s51, 43
	v_writelane_b32 v255, s52, 44
	v_writelane_b32 v255, s53, 45
	v_writelane_b32 v255, s54, 46
	v_writelane_b32 v255, s55, 47
	v_writelane_b32 v255, s56, 48
	v_writelane_b32 v255, s57, 49
	v_writelane_b32 v255, s58, 50
	v_writelane_b32 v255, s59, 51
	v_writelane_b32 v255, s60, 52
	v_writelane_b32 v255, s61, 53
	v_writelane_b32 v255, s62, 54
	v_writelane_b32 v255, s63, 55
	v_writelane_b32 v255, s64, 56
	v_writelane_b32 v255, s65, 57
	v_writelane_b32 v255, s66, 58
	v_writelane_b32 v255, s67, 59
	v_writelane_b32 v255, s68, 60
	v_writelane_b32 v255, s69, 61
	v_writelane_b32 v255, s70, 62
	v_writelane_b32 v255, s71, 63
	v_writelane_b32 v254, s76, 0
	v_writelane_b32 v254, s77, 1
	v_writelane_b32 v254, s80, 2
	v_writelane_b32 v254, s81, 3
	v_writelane_b32 v254, s82, 4
	v_writelane_b32 v254, s83, 5
	v_writelane_b32 v254, s84, 6
	v_writelane_b32 v254, s85, 7
	v_writelane_b32 v254, s86, 8
	v_writelane_b32 v254, s87, 9
	v_writelane_b32 v254, s88, 10
	v_writelane_b32 v254, s89, 11
	v_writelane_b32 v254, s90, 12
	v_writelane_b32 v254, s91, 13
	v_writelane_b32 v254, s92, 14
	v_writelane_b32 v254, s93, 15
	v_writelane_b32 v254, s94, 16
	v_writelane_b32 v254, s95, 17
	v_writelane_b32 v254, s96, 18
	v_writelane_b32 v254, s97, 19
	s_sub_i32 s98, s76, 164
	s_lshl_b32 s98, s98, 3
	s_add_i32 s98, s98, s25
	s_add_i32 s98, s98, 0x7280
	s_movk_i32 s99, 0x2e0
	s_mov_b32 s100, 0x8a20
	s_mov_b32 s101, 2
	s_add_u32 s0, s78, 0xfffffef0
	s_addc_u32 s1, s79, -1
	s_load_dwordx8 s[36:43], s[0:1], 0x40
	s_waitcnt lgkmcnt(0)
	s_branch .Lmy_cvt_entry

.LBB0_790:
	s_cmpk_lg_i32 s33, 0x100
	s_cbranch_scc1 .Lmy_skip_m1
	s_cmp_lt_u32 s24, 64
	s_cbranch_scc1 .Lmy_skip_m1
	s_waitcnt vmcnt(0) lgkmcnt(0)
	s_barrier
	v_writelane_b32 v255, s0, 0
	v_writelane_b32 v255, s1, 1
	v_writelane_b32 v255, s2, 2
	v_writelane_b32 v255, s3, 3
	v_writelane_b32 v255, s4, 4
	v_writelane_b32 v255, s5, 5
	v_writelane_b32 v255, s6, 6
	v_writelane_b32 v255, s7, 7
	v_writelane_b32 v255, s8, 8
	v_writelane_b32 v255, s9, 9
	v_writelane_b32 v255, s10, 10
	v_writelane_b32 v255, s11, 11
	v_writelane_b32 v255, s12, 12
	v_writelane_b32 v255, s13, 13
	v_writelane_b32 v255, s14, 14
	v_writelane_b32 v255, s15, 15
	v_writelane_b32 v255, s16, 16
	v_writelane_b32 v255, s17, 17
	v_writelane_b32 v255, s18, 18
	v_writelane_b32 v255, s19, 19
	v_writelane_b32 v255, s20, 20
	v_writelane_b32 v255, s21, 21
	v_writelane_b32 v255, s22, 22
	v_writelane_b32 v255, s23, 23
	v_writelane_b32 v255, s26, 24
	v_writelane_b32 v255, s27, 25
	v_writelane_b32 v255, s34, 26
	v_writelane_b32 v255, s35, 27
	v_writelane_b32 v255, s36, 28
	v_writelane_b32 v255, s37, 29
	v_writelane_b32 v255, s38, 30
	v_writelane_b32 v255, s39, 31
	v_writelane_b32 v255, s40, 32
	v_writelane_b32 v255, s41, 33
	v_writelane_b32 v255, s42, 34
	v_writelane_b32 v255, s43, 35
	v_writelane_b32 v255, s44, 36
	v_writelane_b32 v255, s45, 37
	v_writelane_b32 v255, s46, 38
	v_writelane_b32 v255, s47, 39
	v_writelane_b32 v255, s48, 40
	v_writelane_b32 v255, s49, 41
	v_writelane_b32 v255, s50, 42
	v_writelane_b32 v255, s51, 43
	v_writelane_b32 v255, s52, 44
	v_writelane_b32 v255, s53, 45
	v_writelane_b32 v255, s54, 46
	v_writelane_b32 v255, s55, 47
	v_writelane_b32 v255, s56, 48
	v_writelane_b32 v255, s57, 49
	v_writelane_b32 v255, s58, 50
	v_writelane_b32 v255, s59, 51
	v_writelane_b32 v255, s60, 52
	v_writelane_b32 v255, s61, 53
	v_writelane_b32 v255, s62, 54
	v_writelane_b32 v255, s63, 55
	v_writelane_b32 v255, s64, 56
	v_writelane_b32 v255, s65, 57
	v_writelane_b32 v255, s66, 58
	v_writelane_b32 v255, s67, 59
	v_writelane_b32 v255, s68, 60
	v_writelane_b32 v255, s69, 61
	v_writelane_b32 v255, s70, 62
	v_writelane_b32 v255, s71, 63
	v_writelane_b32 v254, s76, 0
	v_writelane_b32 v254, s77, 1
	v_writelane_b32 v254, s80, 2
	v_writelane_b32 v254, s81, 3
	v_writelane_b32 v254, s82, 4
	v_writelane_b32 v254, s83, 5
	v_writelane_b32 v254, s84, 6
	v_writelane_b32 v254, s85, 7
	v_writelane_b32 v254, s86, 8
	v_writelane_b32 v254, s87, 9
	v_writelane_b32 v254, s88, 10
	v_writelane_b32 v254, s89, 11
	v_writelane_b32 v254, s90, 12
	v_writelane_b32 v254, s91, 13
	v_writelane_b32 v254, s92, 14
	v_writelane_b32 v254, s93, 15
	v_writelane_b32 v254, s94, 16
	v_writelane_b32 v254, s95, 17
	v_writelane_b32 v254, s96, 18
	v_writelane_b32 v254, s97, 19
	s_sub_i32 s98, s24, 64
	s_lshl_b32 s98, s98, 3
	s_add_i32 s98, s98, s25
	s_add_i32 s98, s98, 0x8a20
	s_movk_i32 s99, 0x600
	s_mov_b32 s100, 0x9900
	s_mov_b32 s101, 7
	s_add_u32 s0, s78, 0xfffffef0
	s_addc_u32 s1, s79, -1
	s_load_dwordx8 s[36:43], s[0:1], 0x40
	s_waitcnt lgkmcnt(0)
	s_branch .Lmy_cvt_entry
.Lmy_back_m1:
	v_readlane_b32 s0, v255, 0
	v_readlane_b32 s1, v255, 1
	v_readlane_b32 s2, v255, 2
	v_readlane_b32 s3, v255, 3
	v_readlane_b32 s4, v255, 4
	v_readlane_b32 s5, v255, 5
	v_readlane_b32 s6, v255, 6
	v_readlane_b32 s7, v255, 7
	v_readlane_b32 s8, v255, 8
	v_readlane_b32 s9, v255, 9
	v_readlane_b32 s10, v255, 10
	v_readlane_b32 s11, v255, 11
	v_readlane_b32 s12, v255, 12
	v_readlane_b32 s13, v255, 13
	v_readlane_b32 s14, v255, 14
	v_readlane_b32 s15, v255, 15
	v_readlane_b32 s16, v255, 16
	v_readlane_b32 s17, v255, 17
	v_readlane_b32 s18, v255, 18
	v_readlane_b32 s19, v255, 19
	v_readlane_b32 s20, v255, 20
	v_readlane_b32 s21, v255, 21
	v_readlane_b32 s22, v255, 22
	v_readlane_b32 s23, v255, 23
	v_readlane_b32 s26, v255, 24
	v_readlane_b32 s27, v255, 25
	v_readlane_b32 s34, v255, 26
	v_readlane_b32 s35, v255, 27
	v_readlane_b32 s36, v255, 28
	v_readlane_b32 s37, v255, 29
	v_readlane_b32 s38, v255, 30
	v_readlane_b32 s39, v255, 31
	v_readlane_b32 s40, v255, 32
	v_readlane_b32 s41, v255, 33
	v_readlane_b32 s42, v255, 34
	v_readlane_b32 s43, v255, 35
	v_readlane_b32 s44, v255, 36
	v_readlane_b32 s45, v255, 37
	v_readlane_b32 s46, v255, 38
	v_readlane_b32 s47, v255, 39
	v_readlane_b32 s48, v255, 40
	v_readlane_b32 s49, v255, 41
	v_readlane_b32 s50, v255, 42
	v_readlane_b32 s51, v255, 43
	v_readlane_b32 s52, v255, 44
	v_readlane_b32 s53, v255, 45
	v_readlane_b32 s54, v255, 46
	v_readlane_b32 s55, v255, 47
	v_readlane_b32 s56, v255, 48
	v_readlane_b32 s57, v255, 49
	v_readlane_b32 s58, v255, 50
	v_readlane_b32 s59, v255, 51
	v_readlane_b32 s60, v255, 52
	v_readlane_b32 s61, v255, 53
	v_readlane_b32 s62, v255, 54
	v_readlane_b32 s63, v255, 55
	v_readlane_b32 s64, v255, 56
	v_readlane_b32 s65, v255, 57
	v_readlane_b32 s66, v255, 58
	v_readlane_b32 s67, v255, 59
	v_readlane_b32 s68, v255, 60
	v_readlane_b32 s69, v255, 61
	v_readlane_b32 s70, v255, 62
	v_readlane_b32 s71, v255, 63
	v_readlane_b32 s76, v254, 0
	v_readlane_b32 s77, v254, 1
	v_readlane_b32 s80, v254, 2
	v_readlane_b32 s81, v254, 3
	v_readlane_b32 s82, v254, 4
	v_readlane_b32 s83, v254, 5
	v_readlane_b32 s84, v254, 6
	v_readlane_b32 s85, v254, 7
	v_readlane_b32 s86, v254, 8
	v_readlane_b32 s87, v254, 9
	v_readlane_b32 s88, v254, 10
	v_readlane_b32 s89, v254, 11
	v_readlane_b32 s90, v254, 12
	v_readlane_b32 s91, v254, 13
	v_readlane_b32 s92, v254, 14
	v_readlane_b32 s93, v254, 15
	v_readlane_b32 s94, v254, 16
	v_readlane_b32 s95, v254, 17
	v_readlane_b32 s96, v254, 18
	v_readlane_b32 s97, v254, 19
.Lmy_skip_m1:
	s_cmp_lt_i32 s31, 8
	s_cbranch_scc1 .LBB0_846
	s_waitcnt vmcnt(0)
	v_readlane_b32 s0, v252, 1
	s_cmp_lg_u32 s0, 0
	s_waitcnt vmcnt(0)
	s_barrier
	s_cbranch_scc1 .LBB0_845
	v_mbcnt_lo_u32_b32 v1, -1, 0
	v_mbcnt_hi_u32_b32 v1, -1, v1
	s_nop 0
	v_cmp_eq_u32_e32 vcc, 0, v1
	s_and_saveexec_b64 s[0:1], vcc
	s_cbranch_execz .LBB0_844
	v_mov_b32_e32 v1, s75
	s_waitcnt vmcnt(0) expcnt(0) lgkmcnt(0)
	ds_read_b32 v3, v1
	ds_read_b32 v1, v1 offset:4
	s_waitcnt lgkmcnt(1)
	v_cmp_ne_u32_e32 vcc, 0, v3
	s_cbranch_vccnz .LBB0_808
	s_load_dwordx2 s[6:7], s[78:79], 0x4
	s_add_u32 s2, s28, 0x4200
	s_addc_u32 s3, s29, 0
	s_add_u32 s4, s28, 0x4400
	s_addc_u32 s5, s29, 0
	s_waitcnt lgkmcnt(0)
	s_mul_i32 s34, s6, s33
	s_add_u32 s6, s28, 0x4500
	s_mul_i32 s34, s34, s7
	s_addc_u32 s7, s29, 0
	s_add_u32 s8, s28, 0x4600
	s_addc_u32 s9, s29, 0
	s_add_u32 s10, s28, 0x4700
	s_addc_u32 s11, s29, 0
	s_add_u32 s12, s28, 0x4800
	s_addc_u32 s13, s29, 0
	s_add_u32 s14, s28, 0x4900
	s_addc_u32 s15, s29, 0
	s_add_u32 s16, s28, 0x4a00
	s_addc_u32 s17, s29, 0
	s_add_u32 s18, s28, 0x4b00
	s_addc_u32 s19, s29, 0
	s_add_u32 s20, s28, 0x4c00
	s_addc_u32 s21, s29, 0
	s_add_u32 s22, s28, 0x4d00
	s_addc_u32 s23, s29, 0
	s_add_u32 s48, s28, 0x4e00
	s_addc_u32 s49, s29, 0
	s_add_u32 s52, s28, 0x4f00
	s_addc_u32 s53, s29, 0
	s_add_u32 s54, s28, 0x5000
	s_addc_u32 s55, s29, 0
	s_add_u32 s56, s28, 0x5100
	s_addc_u32 s57, s29, 0
	s_add_u32 s58, s28, 0x5200
	s_addc_u32 s59, s29, 0
	s_add_u32 s60, s28, 0x5300
	s_addc_u32 s61, s29, 0
	s_mov_b32 s26, 1
	v_mov_b32_e32 v17, 0
	s_branch .LBB0_796

.Lmy_h1_back:
	s_cmp_eq_u32 s101, 8
	s_cbranch_scc1 .Lmy_back_m3
	s_cmp_eq_u32 s101, 3
	s_cbranch_scc1 .Lmy_back_p11
	s_branch .Lmy_h2_back

.LBB0_1255:
	s_cmpk_lg_i32 s33, 0x100
	s_cbranch_scc1 .Lmy_skip_m3
	s_cmp_lt_u32 s24, 64
	s_cbranch_scc1 .Lmy_skip_m3
	s_waitcnt vmcnt(0) lgkmcnt(0)
	s_barrier
	v_writelane_b32 v255, s0, 0
	v_writelane_b32 v255, s1, 1
	v_writelane_b32 v255, s2, 2
	v_writelane_b32 v255, s3, 3
	v_writelane_b32 v255, s4, 4
	v_writelane_b32 v255, s5, 5
	v_writelane_b32 v255, s6, 6
	v_writelane_b32 v255, s7, 7
	v_writelane_b32 v255, s8, 8
	v_writelane_b32 v255, s9, 9
	v_writelane_b32 v255, s10, 10
	v_writelane_b32 v255, s11, 11
	v_writelane_b32 v255, s12, 12
	v_writelane_b32 v255, s13, 13
	v_writelane_b32 v255, s14, 14
	v_writelane_b32 v255, s15, 15
	v_writelane_b32 v255, s16, 16
	v_writelane_b32 v255, s17, 17
	v_writelane_b32 v255, s18, 18
	v_writelane_b32 v255, s19, 19
	v_writelane_b32 v255, s20, 20
	v_writelane_b32 v255, s21, 21
	v_writelane_b32 v255, s22, 22
	v_writelane_b32 v255, s23, 23
	v_writelane_b32 v255, s26, 24
	v_writelane_b32 v255, s27, 25
	v_writelane_b32 v255, s34, 26
	v_writelane_b32 v255, s35, 27
	v_writelane_b32 v255, s36, 28
	v_writelane_b32 v255, s37, 29
	v_writelane_b32 v255, s38, 30
	v_writelane_b32 v255, s39, 31
	v_writelane_b32 v255, s40, 32
	v_writelane_b32 v255, s41, 33
	v_writelane_b32 v255, s42, 34
	v_writelane_b32 v255, s43, 35
	v_writelane_b32 v255, s44, 36
	v_writelane_b32 v255, s45, 37
	v_writelane_b32 v255, s46, 38
	v_writelane_b32 v255, s47, 39
	v_writelane_b32 v255, s48, 40
	v_writelane_b32 v255, s49, 41
	v_writelane_b32 v255, s50, 42
	v_writelane_b32 v255, s51, 43
	v_writelane_b32 v255, s52, 44
	v_writelane_b32 v255, s53, 45
	v_writelane_b32 v255, s54, 46
	v_writelane_b32 v255, s55, 47
	v_writelane_b32 v255, s56, 48
	v_writelane_b32 v255, s57, 49
	v_writelane_b32 v255, s58, 50
	v_writelane_b32 v255, s59, 51
	v_writelane_b32 v255, s60, 52
	v_writelane_b32 v255, s61, 53
	v_writelane_b32 v255, s62, 54
	v_writelane_b32 v255, s63, 55
	v_writelane_b32 v255, s64, 56
	v_writelane_b32 v255, s65, 57
	v_writelane_b32 v255, s66, 58
	v_writelane_b32 v255, s67, 59
	v_writelane_b32 v255, s68, 60
	v_writelane_b32 v255, s69, 61
	v_writelane_b32 v255, s70, 62
	v_writelane_b32 v255, s71, 63
	v_writelane_b32 v254, s76, 0
	v_writelane_b32 v254, s77, 1
	v_writelane_b32 v254, s80, 2
	v_writelane_b32 v254, s81, 3
	v_writelane_b32 v254, s82, 4
	v_writelane_b32 v254, s83, 5
	v_writelane_b32 v254, s84, 6
	v_writelane_b32 v254, s85, 7
	v_writelane_b32 v254, s86, 8
	v_writelane_b32 v254, s87, 9
	v_writelane_b32 v254, s88, 10
	v_writelane_b32 v254, s89, 11
	v_writelane_b32 v254, s90, 12
	v_writelane_b32 v254, s91, 13
	v_writelane_b32 v254, s92, 14
	v_writelane_b32 v254, s93, 15
	v_writelane_b32 v254, s94, 16
	v_writelane_b32 v254, s95, 17
	v_writelane_b32 v254, s96, 18
	v_writelane_b32 v254, s97, 19
	s_sub_i32 s98, s24, 64
	s_lshl_b32 s98, s98, 3
	s_add_i32 s98, s98, s25
	s_add_i32 s98, s98, 0x9900
	s_movk_i32 s99, 0x600
	s_mov_b32 s100, 0xa7dc
	s_mov_b32 s101, 8
	s_add_u32 s0, s78, 0xfffffef0
	s_addc_u32 s1, s79, -1
	s_load_dwordx8 s[36:43], s[0:1], 0x40
	s_waitcnt lgkmcnt(0)
	s_branch .Lmy_h1_fwd
.Lmy_back_m3:
	v_readlane_b32 s0, v255, 0
	v_readlane_b32 s1, v255, 1
	v_readlane_b32 s2, v255, 2
	v_readlane_b32 s3, v255, 3
	v_readlane_b32 s4, v255, 4
	v_readlane_b32 s5, v255, 5
	v_readlane_b32 s6, v255, 6
	v_readlane_b32 s7, v255, 7
	v_readlane_b32 s8, v255, 8
	v_readlane_b32 s9, v255, 9
	v_readlane_b32 s10, v255, 10
	v_readlane_b32 s11, v255, 11
	v_readlane_b32 s12, v255, 12
	v_readlane_b32 s13, v255, 13
	v_readlane_b32 s14, v255, 14
	v_readlane_b32 s15, v255, 15
	v_readlane_b32 s16, v255, 16
	v_readlane_b32 s17, v255, 17
	v_readlane_b32 s18, v255, 18
	v_readlane_b32 s19, v255, 19
	v_readlane_b32 s20, v255, 20
	v_readlane_b32 s21, v255, 21
	v_readlane_b32 s22, v255, 22
	v_readlane_b32 s23, v255, 23
	v_readlane_b32 s26, v255, 24
	v_readlane_b32 s27, v255, 25
	v_readlane_b32 s34, v255, 26
	v_readlane_b32 s35, v255, 27
	v_readlane_b32 s36, v255, 28
	v_readlane_b32 s37, v255, 29
	v_readlane_b32 s38, v255, 30
	v_readlane_b32 s39, v255, 31
	v_readlane_b32 s40, v255, 32
	v_readlane_b32 s41, v255, 33
	v_readlane_b32 s42, v255, 34
	v_readlane_b32 s43, v255, 35
	v_readlane_b32 s44, v255, 36
	v_readlane_b32 s45, v255, 37
	v_readlane_b32 s46, v255, 38
	v_readlane_b32 s47, v255, 39
	v_readlane_b32 s48, v255, 40
	v_readlane_b32 s49, v255, 41
	v_readlane_b32 s50, v255, 42
	v_readlane_b32 s51, v255, 43
	v_readlane_b32 s52, v255, 44
	v_readlane_b32 s53, v255, 45
	v_readlane_b32 s54, v255, 46
	v_readlane_b32 s55, v255, 47
	v_readlane_b32 s56, v255, 48
	v_readlane_b32 s57, v255, 49
	v_readlane_b32 s58, v255, 50
	v_readlane_b32 s59, v255, 51
	v_readlane_b32 s60, v255, 52
	v_readlane_b32 s61, v255, 53
	v_readlane_b32 s62, v255, 54
	v_readlane_b32 s63, v255, 55
	v_readlane_b32 s64, v255, 56
	v_readlane_b32 s65, v255, 57
	v_readlane_b32 s66, v255, 58
	v_readlane_b32 s67, v255, 59
	v_readlane_b32 s68, v255, 60
	v_readlane_b32 s69, v255, 61
	v_readlane_b32 s70, v255, 62
	v_readlane_b32 s71, v255, 63
	v_readlane_b32 s76, v254, 0
	v_readlane_b32 s77, v254, 1
	v_readlane_b32 s80, v254, 2
	v_readlane_b32 s81, v254, 3
	v_readlane_b32 s82, v254, 4
	v_readlane_b32 s83, v254, 5
	v_readlane_b32 s84, v254, 6
	v_readlane_b32 s85, v254, 7
	v_readlane_b32 s86, v254, 8
	v_readlane_b32 s87, v254, 9
	v_readlane_b32 s88, v254, 10
	v_readlane_b32 s89, v254, 11
	v_readlane_b32 s90, v254, 12
	v_readlane_b32 s91, v254, 13
	v_readlane_b32 s92, v254, 14
	v_readlane_b32 s93, v254, 15
	v_readlane_b32 s94, v254, 16
	v_readlane_b32 s95, v254, 17
	v_readlane_b32 s96, v254, 18
	v_readlane_b32 s97, v254, 19
.Lmy_skip_m3:
	s_cmp_lt_i32 s31, 10
	s_cbranch_scc1 .LBB0_1311
	s_waitcnt vmcnt(0)
	v_readlane_b32 s0, v252, 1
	s_cmp_lg_u32 s0, 0
	s_waitcnt vmcnt(0)
	s_barrier
	s_cbranch_scc1 .LBB0_1310
	v_mbcnt_lo_u32_b32 v1, -1, 0
	v_mbcnt_hi_u32_b32 v1, -1, v1
	s_nop 0
	v_cmp_eq_u32_e32 vcc, 0, v1
	s_and_saveexec_b64 s[0:1], vcc
	s_cbranch_execz .LBB0_1309
	v_mov_b32_e32 v1, s75
	s_waitcnt vmcnt(0) expcnt(0) lgkmcnt(0)
	ds_read_b32 v3, v1
	ds_read_b32 v1, v1 offset:4
	s_waitcnt lgkmcnt(1)
	v_cmp_ne_u32_e32 vcc, 0, v3
	s_cbranch_vccnz .LBB0_1273
	s_load_dwordx2 s[6:7], s[78:79], 0x4
	s_add_u32 s2, s28, 0x4200
	s_addc_u32 s3, s29, 0
	s_add_u32 s4, s28, 0x4400
	s_addc_u32 s5, s29, 0
	s_waitcnt lgkmcnt(0)
	s_mul_i32 s34, s6, s33
	s_add_u32 s6, s28, 0x4500
	s_mul_i32 s34, s34, s7
	s_addc_u32 s7, s29, 0
	s_add_u32 s8, s28, 0x4600
	s_addc_u32 s9, s29, 0
	s_add_u32 s10, s28, 0x4700
	s_addc_u32 s11, s29, 0
	s_add_u32 s12, s28, 0x4800
	s_addc_u32 s13, s29, 0
	s_add_u32 s14, s28, 0x4900
	s_addc_u32 s15, s29, 0
	s_add_u32 s16, s28, 0x4a00
	s_addc_u32 s17, s29, 0
	s_add_u32 s18, s28, 0x4b00
	s_addc_u32 s19, s29, 0
	s_add_u32 s20, s28, 0x4c00
	s_addc_u32 s21, s29, 0
	s_add_u32 s22, s28, 0x4d00
	s_addc_u32 s23, s29, 0
	s_add_u32 s44, s28, 0x4e00
	s_addc_u32 s45, s29, 0
	s_add_u32 s46, s28, 0x4f00
	s_addc_u32 s47, s29, 0
	s_add_u32 s48, s28, 0x5000
	s_addc_u32 s49, s29, 0
	s_add_u32 s50, s28, 0x5100
	s_addc_u32 s51, s29, 0
	s_add_u32 s52, s28, 0x5200
	s_addc_u32 s53, s29, 0
	s_add_u32 s54, s28, 0x5300
	s_addc_u32 s55, s29, 0
	s_mov_b32 s26, 1
	v_mov_b32_e32 v17, 0
	s_branch .LBB0_1261

.LBB0_1571:
	s_cmpk_lg_i32 s33, 0x100
	s_cbranch_scc1 .Lmy_skip_p11
	s_cmp_lt_u32 s76, 108
	s_cbranch_scc1 .Lmy_skip_p11
	s_waitcnt vmcnt(0) lgkmcnt(0)
	s_barrier
	v_writelane_b32 v255, s0, 0
	v_writelane_b32 v255, s1, 1
	v_writelane_b32 v255, s2, 2
	v_writelane_b32 v255, s3, 3
	v_writelane_b32 v255, s4, 4
	v_writelane_b32 v255, s5, 5
	v_writelane_b32 v255, s6, 6
	v_writelane_b32 v255, s7, 7
	v_writelane_b32 v255, s8, 8
	v_writelane_b32 v255, s9, 9
	v_writelane_b32 v255, s10, 10
	v_writelane_b32 v255, s11, 11
	v_writelane_b32 v255, s12, 12
	v_writelane_b32 v255, s13, 13
	v_writelane_b32 v255, s14, 14
	v_writelane_b32 v255, s15, 15
	v_writelane_b32 v255, s16, 16
	v_writelane_b32 v255, s17, 17
	v_writelane_b32 v255, s18, 18
	v_writelane_b32 v255, s19, 19
	v_writelane_b32 v255, s20, 20
	v_writelane_b32 v255, s21, 21
	v_writelane_b32 v255, s22, 22
	v_writelane_b32 v255, s23, 23
	v_writelane_b32 v255, s26, 24
	v_writelane_b32 v255, s27, 25
	v_writelane_b32 v255, s34, 26
	v_writelane_b32 v255, s35, 27
	v_writelane_b32 v255, s36, 28
	v_writelane_b32 v255, s37, 29
	v_writelane_b32 v255, s38, 30
	v_writelane_b32 v255, s39, 31
	v_writelane_b32 v255, s40, 32
	v_writelane_b32 v255, s41, 33
	v_writelane_b32 v255, s42, 34
	v_writelane_b32 v255, s43, 35
	v_writelane_b32 v255, s44, 36
	v_writelane_b32 v255, s45, 37
	v_writelane_b32 v255, s46, 38
	v_writelane_b32 v255, s47, 39
	v_writelane_b32 v255, s48, 40
	v_writelane_b32 v255, s49, 41
	v_writelane_b32 v255, s50, 42
	v_writelane_b32 v255, s51, 43
	v_writelane_b32 v255, s52, 44
	v_writelane_b32 v255, s53, 45
	v_writelane_b32 v255, s54, 46
	v_writelane_b32 v255, s55, 47
	v_writelane_b32 v255, s56, 48
	v_writelane_b32 v255, s57, 49
	v_writelane_b32 v255, s58, 50
	v_writelane_b32 v255, s59, 51
	v_writelane_b32 v255, s60, 52
	v_writelane_b32 v255, s61, 53
	v_writelane_b32 v255, s62, 54
	v_writelane_b32 v255, s63, 55
	v_writelane_b32 v255, s64, 56
	v_writelane_b32 v255, s65, 57
	v_writelane_b32 v255, s66, 58
	v_writelane_b32 v255, s67, 59
	v_writelane_b32 v255, s68, 60
	v_writelane_b32 v255, s69, 61
	v_writelane_b32 v255, s70, 62
	v_writelane_b32 v255, s71, 63
	v_writelane_b32 v254, s76, 0
	v_writelane_b32 v254, s77, 1
	v_writelane_b32 v254, s80, 2
	v_writelane_b32 v254, s81, 3
	v_writelane_b32 v254, s82, 4
	v_writelane_b32 v254, s83, 5
	v_writelane_b32 v254, s84, 6
	v_writelane_b32 v254, s85, 7
	v_writelane_b32 v254, s86, 8
	v_writelane_b32 v254, s87, 9
	v_writelane_b32 v254, s88, 10
	v_writelane_b32 v254, s89, 11
	v_writelane_b32 v254, s90, 12
	v_writelane_b32 v254, s91, 13
	v_writelane_b32 v254, s92, 14
	v_writelane_b32 v254, s93, 15
	v_writelane_b32 v254, s94, 16
	v_writelane_b32 v254, s95, 17
	v_writelane_b32 v254, s96, 18
	v_writelane_b32 v254, s97, 19
	s_sub_i32 s98, s76, 108
	s_lshl_b32 s98, s98, 3
	s_add_i32 s98, s98, s25
	s_add_i32 s98, s98, 0xa7dc
	s_movk_i32 s99, 0x4a0
	s_mov_b32 s100, 0xcd00
	s_mov_b32 s101, 3
	s_add_u32 s0, s78, 0xfffffef0
	s_addc_u32 s1, s79, -1
	s_load_dwordx8 s[36:43], s[0:1], 0x40
	s_waitcnt lgkmcnt(0)
	s_branch .Lmy_h1_fwd

.Lmy_h2_back:
	s_cmp_eq_u32 s101, 4
	s_cbranch_scc1 .Lmy_back_p14
	s_cmp_eq_u32 s101, 5
	s_cbranch_scc1 .Lmy_back_p17
	s_branch .Lmy_back_l18

.LBB0_2241:
	s_waitcnt vmcnt(0)
	s_barrier
	s_cmpk_lg_i32 s33, 0x100
	s_cbranch_scc1 .Lmy_skip_p17
	s_cmp_lt_u32 s76, 48
	s_cbranch_scc1 .Lmy_skip_p17
	s_waitcnt vmcnt(0) lgkmcnt(0)
	s_barrier
	v_writelane_b32 v255, s0, 0
	v_writelane_b32 v255, s1, 1
	v_writelane_b32 v255, s2, 2
	v_writelane_b32 v255, s3, 3
	v_writelane_b32 v255, s4, 4
	v_writelane_b32 v255, s5, 5
	v_writelane_b32 v255, s6, 6
	v_writelane_b32 v255, s7, 7
	v_writelane_b32 v255, s8, 8
	v_writelane_b32 v255, s9, 9
	v_writelane_b32 v255, s10, 10
	v_writelane_b32 v255, s11, 11
	v_writelane_b32 v255, s12, 12
	v_writelane_b32 v255, s13, 13
	v_writelane_b32 v255, s14, 14
	v_writelane_b32 v255, s15, 15
	v_writelane_b32 v255, s16, 16
	v_writelane_b32 v255, s17, 17
	v_writelane_b32 v255, s18, 18
	v_writelane_b32 v255, s19, 19
	v_writelane_b32 v255, s20, 20
	v_writelane_b32 v255, s21, 21
	v_writelane_b32 v255, s22, 22
	v_writelane_b32 v255, s23, 23
	v_writelane_b32 v255, s26, 24
	v_writelane_b32 v255, s27, 25
	v_writelane_b32 v255, s34, 26
	v_writelane_b32 v255, s35, 27
	v_writelane_b32 v255, s36, 28
	v_writelane_b32 v255, s37, 29
	v_writelane_b32 v255, s38, 30
	v_writelane_b32 v255, s39, 31
	v_writelane_b32 v255, s40, 32
	v_writelane_b32 v255, s41, 33
	v_writelane_b32 v255, s42, 34
	v_writelane_b32 v255, s43, 35
	v_writelane_b32 v255, s44, 36
	v_writelane_b32 v255, s45, 37
	v_writelane_b32 v255, s46, 38
	v_writelane_b32 v255, s47, 39
	v_writelane_b32 v255, s48, 40
	v_writelane_b32 v255, s49, 41
	v_writelane_b32 v255, s50, 42
	v_writelane_b32 v255, s51, 43
	v_writelane_b32 v255, s52, 44
	v_writelane_b32 v255, s53, 45
	v_writelane_b32 v255, s54, 46
	v_writelane_b32 v255, s55, 47
	v_writelane_b32 v255, s56, 48
	v_writelane_b32 v255, s57, 49
	v_writelane_b32 v255, s58, 50
	v_writelane_b32 v255, s59, 51
	v_writelane_b32 v255, s60, 52
	v_writelane_b32 v255, s61, 53
	v_writelane_b32 v255, s62, 54
	v_writelane_b32 v255, s63, 55
	v_writelane_b32 v255, s64, 56
	v_writelane_b32 v255, s65, 57
	v_writelane_b32 v255, s66, 58
	v_writelane_b32 v255, s67, 59
	v_writelane_b32 v255, s68, 60
	v_writelane_b32 v255, s69, 61
	v_writelane_b32 v255, s70, 62
	v_writelane_b32 v255, s71, 63
	v_writelane_b32 v254, s76, 0
	v_writelane_b32 v254, s77, 1
	v_writelane_b32 v254, s80, 2
	v_writelane_b32 v254, s81, 3
	v_writelane_b32 v254, s82, 4
	v_writelane_b32 v254, s83, 5
	v_writelane_b32 v254, s84, 6
	v_writelane_b32 v254, s85, 7
	v_writelane_b32 v254, s86, 8
	v_writelane_b32 v254, s87, 9
	v_writelane_b32 v254, s88, 10
	v_writelane_b32 v254, s89, 11
	v_writelane_b32 v254, s90, 12
	v_writelane_b32 v254, s91, 13
	v_writelane_b32 v254, s92, 14
	v_writelane_b32 v254, s93, 15
	v_writelane_b32 v254, s94, 16
	v_writelane_b32 v254, s95, 17
	v_writelane_b32 v254, s96, 18
	v_writelane_b32 v254, s97, 19
	s_sub_i32 s98, s76, 48
	s_lshl_b32 s98, s98, 3
	s_add_i32 s98, s98, s25
	s_add_i32 s98, s98, 0xfa00
	s_movk_i32 s99, 0x680
	s_mov_b32 s100, 0x12adc
	s_mov_b32 s101, 5
	s_add_u32 s0, s78, 0xfffffef0
	s_addc_u32 s1, s79, -1
	s_load_dwordx8 s[36:43], s[0:1], 0x40
	s_waitcnt lgkmcnt(0)
	s_branch .Lmy_h2_fwd

.LBB0_2319:
	s_cmpk_lg_i32 s33, 0x100
	s_cbranch_scc1 .Lmy_skip_l18
	s_cmp_lt_u32 s24, 64
	s_cbranch_scc1 .Lmy_skip_l18
	s_waitcnt vmcnt(0) lgkmcnt(0)
	s_barrier
	v_writelane_b32 v255, s0, 0
	v_writelane_b32 v255, s1, 1
	v_writelane_b32 v255, s2, 2
	v_writelane_b32 v255, s3, 3
	v_writelane_b32 v255, s4, 4
	v_writelane_b32 v255, s5, 5
	v_writelane_b32 v255, s6, 6
	v_writelane_b32 v255, s7, 7
	v_writelane_b32 v255, s8, 8
	v_writelane_b32 v255, s9, 9
	v_writelane_b32 v255, s10, 10
	v_writelane_b32 v255, s11, 11
	v_writelane_b32 v255, s12, 12
	v_writelane_b32 v255, s13, 13
	v_writelane_b32 v255, s14, 14
	v_writelane_b32 v255, s15, 15
	v_writelane_b32 v255, s16, 16
	v_writelane_b32 v255, s17, 17
	v_writelane_b32 v255, s18, 18
	v_writelane_b32 v255, s19, 19
	v_writelane_b32 v255, s20, 20
	v_writelane_b32 v255, s21, 21
	v_writelane_b32 v255, s22, 22
	v_writelane_b32 v255, s23, 23
	v_writelane_b32 v255, s26, 24
	v_writelane_b32 v255, s27, 25
	v_writelane_b32 v255, s34, 26
	v_writelane_b32 v255, s35, 27
	v_writelane_b32 v255, s36, 28
	v_writelane_b32 v255, s37, 29
	v_writelane_b32 v255, s38, 30
	v_writelane_b32 v255, s39, 31
	v_writelane_b32 v255, s40, 32
	v_writelane_b32 v255, s41, 33
	v_writelane_b32 v255, s42, 34
	v_writelane_b32 v255, s43, 35
	v_writelane_b32 v255, s44, 36
	v_writelane_b32 v255, s45, 37
	v_writelane_b32 v255, s46, 38
	v_writelane_b32 v255, s47, 39
	v_writelane_b32 v255, s48, 40
	v_writelane_b32 v255, s49, 41
	v_writelane_b32 v255, s50, 42
	v_writelane_b32 v255, s51, 43
	v_writelane_b32 v255, s52, 44
	v_writelane_b32 v255, s53, 45
	v_writelane_b32 v255, s54, 46
	v_writelane_b32 v255, s55, 47
	v_writelane_b32 v255, s56, 48
	v_writelane_b32 v255, s57, 49
	v_writelane_b32 v255, s58, 50
	v_writelane_b32 v255, s59, 51
	v_writelane_b32 v255, s60, 52
	v_writelane_b32 v255, s61, 53
	v_writelane_b32 v255, s62, 54
	v_writelane_b32 v255, s63, 55
	v_writelane_b32 v255, s64, 56
	v_writelane_b32 v255, s65, 57
	v_writelane_b32 v255, s66, 58
	v_writelane_b32 v255, s67, 59
	v_writelane_b32 v255, s68, 60
	v_writelane_b32 v255, s69, 61
	v_writelane_b32 v255, s70, 62
	v_writelane_b32 v255, s71, 63
	v_writelane_b32 v254, s76, 0
	v_writelane_b32 v254, s77, 1
	v_writelane_b32 v254, s80, 2
	v_writelane_b32 v254, s81, 3
	v_writelane_b32 v254, s82, 4
	v_writelane_b32 v254, s83, 5
	v_writelane_b32 v254, s84, 6
	v_writelane_b32 v254, s85, 7
	v_writelane_b32 v254, s86, 8
	v_writelane_b32 v254, s87, 9
	v_writelane_b32 v254, s88, 10
	v_writelane_b32 v254, s89, 11
	v_writelane_b32 v254, s90, 12
	v_writelane_b32 v254, s91, 13
	v_writelane_b32 v254, s92, 14
	v_writelane_b32 v254, s93, 15
	v_writelane_b32 v254, s94, 16
	v_writelane_b32 v254, s95, 17
	v_writelane_b32 v254, s96, 18
	v_writelane_b32 v254, s97, 19
	s_sub_i32 s98, s24, 64
	s_lshl_b32 s98, s98, 3
	s_add_i32 s98, s98, s25
	s_add_i32 s98, s98, 0x12adc
	s_movk_i32 s99, 0x600
	s_mov_b32 s100, 0x13a80
	s_mov_b32 s101, 10
	s_add_u32 s0, s78, 0xfffffef0
	s_addc_u32 s1, s79, -1
	s_load_dwordx8 s[36:43], s[0:1], 0x40
	s_waitcnt lgkmcnt(0)
	s_branch .Lmy_h2_fwd
.Lmy_back_l18:
	v_readlane_b32 s0, v255, 0
	v_readlane_b32 s1, v255, 1
	v_readlane_b32 s2, v255, 2
	v_readlane_b32 s3, v255, 3
	v_readlane_b32 s4, v255, 4
	v_readlane_b32 s5, v255, 5
	v_readlane_b32 s6, v255, 6
	v_readlane_b32 s7, v255, 7
	v_readlane_b32 s8, v255, 8
	v_readlane_b32 s9, v255, 9
	v_readlane_b32 s10, v255, 10
	v_readlane_b32 s11, v255, 11
	v_readlane_b32 s12, v255, 12
	v_readlane_b32 s13, v255, 13
	v_readlane_b32 s14, v255, 14
	v_readlane_b32 s15, v255, 15
	v_readlane_b32 s16, v255, 16
	v_readlane_b32 s17, v255, 17
	v_readlane_b32 s18, v255, 18
	v_readlane_b32 s19, v255, 19
	v_readlane_b32 s20, v255, 20
	v_readlane_b32 s21, v255, 21
	v_readlane_b32 s22, v255, 22
	v_readlane_b32 s23, v255, 23
	v_readlane_b32 s26, v255, 24
	v_readlane_b32 s27, v255, 25
	v_readlane_b32 s34, v255, 26
	v_readlane_b32 s35, v255, 27
	v_readlane_b32 s36, v255, 28
	v_readlane_b32 s37, v255, 29
	v_readlane_b32 s38, v255, 30
	v_readlane_b32 s39, v255, 31
	v_readlane_b32 s40, v255, 32
	v_readlane_b32 s41, v255, 33
	v_readlane_b32 s42, v255, 34
	v_readlane_b32 s43, v255, 35
	v_readlane_b32 s44, v255, 36
	v_readlane_b32 s45, v255, 37
	v_readlane_b32 s46, v255, 38
	v_readlane_b32 s47, v255, 39
	v_readlane_b32 s48, v255, 40
	v_readlane_b32 s49, v255, 41
	v_readlane_b32 s50, v255, 42
	v_readlane_b32 s51, v255, 43
	v_readlane_b32 s52, v255, 44
	v_readlane_b32 s53, v255, 45
	v_readlane_b32 s54, v255, 46
	v_readlane_b32 s55, v255, 47
	v_readlane_b32 s56, v255, 48
	v_readlane_b32 s57, v255, 49
	v_readlane_b32 s58, v255, 50
	v_readlane_b32 s59, v255, 51
	v_readlane_b32 s60, v255, 52
	v_readlane_b32 s61, v255, 53
	v_readlane_b32 s62, v255, 54
	v_readlane_b32 s63, v255, 55
	v_readlane_b32 s64, v255, 56
	v_readlane_b32 s65, v255, 57
	v_readlane_b32 s66, v255, 58
	v_readlane_b32 s67, v255, 59
	v_readlane_b32 s68, v255, 60
	v_readlane_b32 s69, v255, 61
	v_readlane_b32 s70, v255, 62
	v_readlane_b32 s71, v255, 63
	v_readlane_b32 s76, v254, 0
	v_readlane_b32 s77, v254, 1
	v_readlane_b32 s80, v254, 2
	v_readlane_b32 s81, v254, 3
	v_readlane_b32 s82, v254, 4
	v_readlane_b32 s83, v254, 5
	v_readlane_b32 s84, v254, 6
	v_readlane_b32 s85, v254, 7
	v_readlane_b32 s86, v254, 8
	v_readlane_b32 s87, v254, 9
	v_readlane_b32 s88, v254, 10
	v_readlane_b32 s89, v254, 11
	v_readlane_b32 s90, v254, 12
	v_readlane_b32 s91, v254, 13
	v_readlane_b32 s92, v254, 14
	v_readlane_b32 s93, v254, 15
	v_readlane_b32 s94, v254, 16
	v_readlane_b32 s95, v254, 17
	v_readlane_b32 s96, v254, 18
	v_readlane_b32 s97, v254, 19
.Lmy_skip_l18:
	s_cmp_lt_i32 s31, 20
	s_cbranch_scc1 .LBB0_2375
	s_waitcnt vmcnt(0)
	v_readlane_b32 s0, v252, 1
	s_cmp_lg_u32 s0, 0
	s_waitcnt vmcnt(0)
	s_barrier
	s_cbranch_scc1 .LBB0_2374
	v_mbcnt_lo_u32_b32 v1, -1, 0
	v_mbcnt_hi_u32_b32 v1, -1, v1
	s_nop 0
	v_cmp_eq_u32_e32 vcc, 0, v1
	s_and_saveexec_b64 s[0:1], vcc
	s_cbranch_execz .LBB0_2373
	v_mov_b32_e32 v1, s75
	s_waitcnt vmcnt(0) expcnt(0) lgkmcnt(0)
	ds_read_b32 v3, v1
	ds_read_b32 v1, v1 offset:4
	s_waitcnt lgkmcnt(1)
	v_cmp_ne_u32_e32 vcc, 0, v3
	s_cbranch_vccnz .LBB0_2337
	s_load_dwordx2 s[6:7], s[78:79], 0x4
	s_add_u32 s2, s28, 0x4200
	s_addc_u32 s3, s29, 0
	s_add_u32 s4, s28, 0x4400
	s_addc_u32 s5, s29, 0
	s_waitcnt lgkmcnt(0)
	s_mul_i32 s34, s6, s33
	s_add_u32 s6, s28, 0x4500
	s_mul_i32 s34, s34, s7
	s_addc_u32 s7, s29, 0
	s_add_u32 s8, s28, 0x4600
	s_addc_u32 s9, s29, 0
	s_add_u32 s10, s28, 0x4700
	s_addc_u32 s11, s29, 0
	s_add_u32 s12, s28, 0x4800
	s_addc_u32 s13, s29, 0
	s_add_u32 s14, s28, 0x4900
	s_addc_u32 s15, s29, 0
	s_add_u32 s16, s28, 0x4a00
	s_addc_u32 s17, s29, 0
	s_add_u32 s18, s28, 0x4b00
	s_addc_u32 s19, s29, 0
	s_add_u32 s20, s28, 0x4c00
	s_addc_u32 s21, s29, 0
	s_add_u32 s22, s28, 0x4d00
	s_addc_u32 s23, s29, 0
	s_add_u32 s44, s28, 0x4e00
	s_addc_u32 s45, s29, 0
	s_add_u32 s46, s28, 0x4f00
	s_addc_u32 s47, s29, 0
	s_add_u32 s48, s28, 0x5000
	s_addc_u32 s49, s29, 0
	s_add_u32 s50, s28, 0x5100
	s_addc_u32 s51, s29, 0
	s_add_u32 s52, s28, 0x5200
	s_addc_u32 s53, s29, 0
	s_add_u32 s54, s28, 0x5300
	s_addc_u32 s55, s29, 0
	s_mov_b32 s26, 1
	v_mov_b32_e32 v17, 0
	s_branch .LBB0_2325
